# lru_item: the four serialized groups of per-channel parameter loads issued together at the top of the item block (one round trip instead of four)
# speedup vs baseline: 1.0068x; 1.0052x over previous
; __device__ __forceinline__ bf16_t f2bf(float f) { return (bf16_t)(pk2(f, 0.f) & 0xffffu); }
; __device__ __forceinline__ float bf2f(unsigned b) { return __uint_as_float(b << 16); }
; __device__ __forceinline__ void lru_item(const Params& p, int l, int item, LAS unsigned char* lds) {
;     ...
;     bf16x8 wa0[4], wa1[4], wx0[4], wx1[4];
;     { const bf16_t* wap = p.waT + (((size_t)l * 4 + h) * 64 + fr) * 64 + fq * 8; const bf16_t* wxp = p.wxT + (((size_t)l * 4 + h) * 64 + fr) * 64 + fq * 8;
; #pragma unroll
;       for (int jt = 0; jt < 4; ++jt) { wa0[jt] = *(const bf16x8*)(wap + jt * 1024); wa1[jt] = *(const bf16x8*)(wap + jt * 1024 + 32); wx0[jt] = *(const bf16x8*)(wxp + jt * 1024); wx1[jt] = *(const bf16x8*)(wxp + jt * 1024 + 32); } }
;     { const float cb = p.conv_b[l * 256 + ch], cw0 = p.conv_w[(l * 4 + 0) * 256 + ch], cw1 = p.conv_w[(l * 4 + 1) * 256 + ch], cw2 = p.conv_w[(l * 4 + 2) * 256 + ch], cw3 = p.conv_w[(l * 4 + 3) * 256 + ch];
; #pragma unroll
;       for (int i = 0; i < 16; ++i) { const float xc = cb + bf2f(xr[i]) * cw0 + bf2f(xr[i + 1]) * cw1 + bf2f(xr[i + 2]) * cw2 + bf2f(xr[i + 3]) * cw3; xa[i * 72 + lane] = f2bf(xc); xf[i * 66 + lane] = xc; } }
;     ...
;           const int cj = l * 256 + h * 64 + jt * 16 + fr; const float bav = p.ba[cj], bxv = p.bx[cj], sp = p.spl[cj];
.LBB0_393:
	s_or_b64 exec, exec, s[74:75]
	s_movk_i32 s4, 0x2a00
	v_and_b32_e32 v91, 15, v1
	s_or_b32 s98, s16, s40
	v_or_b32_e32 v148, s98, v91
	v_ashrrev_i32_e32 v149, 31, v148
	v_lshlrev_b64 v[148:149], 2, v[148:149]
	v_lshl_add_u64 v[150:151], s[30:31], 0, v[148:149]
	v_lshl_add_u64 v[152:153], s[6:7], 0, v[148:149]
	v_lshl_add_u64 v[154:155], s[34:35], 0, v[148:149]
	global_load_dword v156, v[150:151], off
	global_load_dword v157, v[152:153], off
	global_load_dword v158, v[154:155], off
	global_load_dword v159, v[150:151], off offset:64
	global_load_dword v160, v[152:153], off offset:64
	global_load_dword v161, v[154:155], off offset:64
	global_load_dword v162, v[150:151], off offset:128
	global_load_dword v163, v[152:153], off offset:128
	global_load_dword v164, v[154:155], off offset:128
	global_load_dword v165, v[150:151], off offset:192
	global_load_dword v166, v[152:153], off offset:192
	global_load_dword v167, v[154:155], off offset:192
	v_mul_lo_u32 v4, v0, s4
	s_or_b32 s4, s12, s16
	v_add_u32_e32 v79, 0, v4
	v_or_b32_e32 v4, s4, v91
	v_mov_b32_e32 v5, s13
	v_lshlrev_b64 v[4:5], 7, v[4:5]
	v_lshl_add_u64 v[6:7], s[70:71], 0, v[4:5]
	v_and_b32_e32 v20, 48, v3
	v_mov_b32_e32 v21, v2
	v_lshl_add_u64 v[6:7], v[6:7], 0, v[20:21]
	v_lshl_add_u64 v[4:5], s[36:37], 0, v[4:5]
	v_add_co_u32_e32 v8, vcc, s80, v6
	v_lshl_add_u64 v[4:5], v[4:5], 0, v[20:21]
	s_nop 0
	v_addc_co_u32_e32 v9, vcc, 0, v7, vcc
	v_or_b32_e32 v100, s40, v78
	v_mov_b32_e32 v98, s17
	v_mov_b32_e32 v99, s22
	v_add_co_u32_e32 v16, vcc, s80, v4
	v_ashrrev_i32_e32 v101, 31, v100
	s_nop 0
	v_addc_co_u32_e32 v17, vcc, 0, v5, vcc
	v_lshl_add_u64 v[98:99], v[100:101], 2, v[98:99]
	global_load_dwordx4 v[60:63], v[6:7], off
	global_load_dwordx4 v[64:67], v[6:7], off offset:64
	global_load_dwordx4 v[68:71], v[4:5], off
	global_load_dwordx4 v[72:75], v[4:5], off offset:64
	global_load_dwordx4 v[44:47], v[6:7], off offset:2048
	global_load_dwordx4 v[48:51], v[6:7], off offset:2112
	global_load_dwordx4 v[52:55], v[4:5], off offset:2048
	global_load_dwordx4 v[56:59], v[4:5], off offset:2112
	global_load_dwordx4 v[28:31], v[8:9], off
	global_load_dwordx4 v[32:35], v[8:9], off offset:64
	global_load_dwordx4 v[36:39], v[16:17], off
	global_load_dwordx4 v[40:43], v[16:17], off offset:64
	s_nop 0
	global_load_dwordx4 v[4:7], v[8:9], off offset:2048
	s_nop 0
	global_load_dwordx4 v[8:11], v[8:9], off offset:2112
	s_nop 0
	global_load_dwordx4 v[12:15], v[16:17], off offset:2048
	s_nop 0
	global_load_dwordx4 v[16:19], v[16:17], off offset:2112
	v_mov_b32_e32 v96, s33
	global_load_dword v21, v[98:99], off
	v_or_b32_e32 v98, s87, v78
	v_mov_b32_e32 v97, s44
	v_ashrrev_i32_e32 v99, 31, v98
	v_lshl_add_u64 v[96:97], v[98:99], 2, v[96:97]
	global_load_dword v98, v[96:97], off
	global_load_dword v99, v[96:97], off offset:1024
	global_load_dword v100, v[96:97], off offset:2048
	s_nop 0
	global_load_dword v96, v[96:97], off offset:3072
	v_lshlrev_b32_e32 v78, 1, v3
	v_add_u32_e32 v97, v79, v78
	v_add_u32_e32 v80, v97, v78
	s_or_b32 s4, s16, s40
	s_mov_b32 s16, 0xf800000
	v_lshrrev_b32_e32 v92, 4, v3
	v_lshl_add_u32 v1, v1, 3, 0
	v_add_u32_e32 v1, 0x15000, v1
	s_waitcnt vmcnt(3)
	v_fma_f32 v88, v88, v98, v21
	s_waitcnt vmcnt(2)
	v_fmac_f32_e32 v88, v87, v99
	v_fma_f32 v87, v87, v98, v21
	s_waitcnt vmcnt(1)
	v_fmac_f32_e32 v88, v85, v100
	v_fmac_f32_e32 v87, v85, v99
	s_waitcnt vmcnt(0)
	v_fmac_f32_e32 v88, v83, v96
	v_cvt_pk_bf16_f32 v101, v88, v2
	v_fmac_f32_e32 v87, v83, v100
	v_fma_f32 v85, v85, v98, v21
	ds_write_b16 v97, v101
	v_fmac_f32_e32 v87, v26, v96
	v_cvt_pk_bf16_f32 v101, v87, v2
	v_fmac_f32_e32 v85, v83, v99
	v_fma_f32 v83, v83, v98, v21
	ds_write_b16 v97, v101 offset:144
	v_add_u32_e32 v101, 0x800, v80
	v_fmac_f32_e32 v85, v26, v100
	v_fmac_f32_e32 v83, v26, v99
	ds_write2_b32 v101, v88, v87 offset0:64 offset1:130
	v_fmac_f32_e32 v85, v22, v96
	v_cvt_pk_bf16_f32 v87, v85, v2
	v_fmac_f32_e32 v83, v22, v100
	v_fma_f32 v26, v26, v98, v21
	ds_write_b16 v97, v87 offset:288
	v_fmac_f32_e32 v83, v24, v96
	v_cvt_pk_bf16_f32 v87, v83, v2
	v_fmac_f32_e32 v26, v22, v99
	v_fma_f32 v22, v22, v98, v21
	ds_write_b16 v97, v87 offset:432
	v_add_u32_e32 v87, 0xa00, v80
	v_fmac_f32_e32 v26, v24, v100
	v_fmac_f32_e32 v22, v24, v99
	ds_write2_b32 v87, v85, v83 offset0:68 offset1:134
	v_fmac_f32_e32 v26, v23, v96
	v_cvt_pk_bf16_f32 v83, v26, v2
	v_fmac_f32_e32 v22, v23, v100
	ds_write_b16 v97, v83 offset:576
	v_fmac_f32_e32 v22, v27, v96
	v_cvt_pk_bf16_f32 v83, v22, v2
	ds_write_b16 v97, v83 offset:720
	v_add_u32_e32 v83, 0xc00, v80
	ds_write2_b32 v83, v26, v22 offset0:72 offset1:138
	v_fma_f32 v22, v24, v98, v21
	v_fmac_f32_e32 v22, v23, v99
	v_fma_f32 v23, v23, v98, v21
	v_fmac_f32_e32 v22, v27, v100
	v_fmac_f32_e32 v23, v27, v99
	v_fmac_f32_e32 v22, v25, v96
	v_cvt_pk_bf16_f32 v24, v22, v2
	v_fmac_f32_e32 v23, v25, v100
	ds_write_b16 v97, v24 offset:864
	v_fmac_f32_e32 v23, v82, v96
	v_cvt_pk_bf16_f32 v24, v23, v2
	ds_write_b16 v97, v24 offset:1008
	v_add_u32_e32 v24, 0xe00, v80
	ds_write2_b32 v24, v22, v23 offset0:76 offset1:142
	v_fma_f32 v22, v27, v98, v21
	v_fmac_f32_e32 v22, v25, v99
	v_fmac_f32_e32 v22, v82, v100
	v_fmac_f32_e32 v22, v81, v96
	v_cvt_pk_bf16_f32 v23, v22, v2
	ds_write_b16 v97, v23 offset:1152
	v_fma_f32 v23, v25, v98, v21
	v_fmac_f32_e32 v23, v82, v99
	v_fmac_f32_e32 v23, v81, v100
	v_fmac_f32_e32 v23, v86, v96
	v_cvt_pk_bf16_f32 v24, v23, v2
	ds_write_b16 v97, v24 offset:1296
	v_add_u32_e32 v24, 0x1000, v80
	ds_write2_b32 v24, v22, v23 offset0:80 offset1:146
	v_fma_f32 v22, v82, v98, v21
	v_fmac_f32_e32 v22, v81, v99
	v_fmac_f32_e32 v22, v86, v100
	v_fmac_f32_e32 v22, v84, v96
	v_cvt_pk_bf16_f32 v23, v22, v2
	ds_write_b16 v97, v23 offset:1440
	v_fma_f32 v23, v81, v98, v21
	v_fmac_f32_e32 v23, v86, v99
	v_fmac_f32_e32 v23, v84, v100
	v_fmac_f32_e32 v23, v90, v96
	v_cvt_pk_bf16_f32 v24, v23, v2
	ds_write_b16 v97, v24 offset:1584
	v_add_u32_e32 v24, 0x1200, v80
	ds_write2_b32 v24, v22, v23 offset0:84 offset1:150
	v_fma_f32 v22, v86, v98, v21
	v_fmac_f32_e32 v22, v84, v99
	v_fmac_f32_e32 v22, v90, v100
	v_fmac_f32_e32 v22, v89, v96
	v_cvt_pk_bf16_f32 v23, v22, v2
	ds_write_b16 v97, v23 offset:1728
	v_fma_f32 v23, v84, v98, v21
	v_fmac_f32_e32 v23, v90, v99
	v_fmac_f32_e32 v23, v89, v100
	v_fmac_f32_e32 v23, v94, v96
	v_cvt_pk_bf16_f32 v24, v23, v2
	ds_write_b16 v97, v24 offset:1872
	v_add_u32_e32 v24, 0x1400, v80
	ds_write2_b32 v24, v22, v23 offset0:88 offset1:154
	v_fma_f32 v22, v90, v98, v21
	v_fmac_f32_e32 v22, v89, v99
	v_fmac_f32_e32 v21, v89, v98
	v_fmac_f32_e32 v22, v94, v100
	v_fmac_f32_e32 v21, v94, v99
	v_fmac_f32_e32 v22, v93, v96
	v_cvt_pk_bf16_f32 v23, v22, v2
	v_fmac_f32_e32 v21, v93, v100
	ds_write_b16 v97, v23 offset:2016
	v_fmac_f32_e32 v21, v95, v96
	v_cvt_pk_bf16_f32 v23, v21, v2
	ds_write_b16 v97, v23 offset:2160
	v_add_u32_e32 v23, 0x1600, v80
	ds_write2_b32 v23, v22, v21 offset0:92 offset1:158
	v_mul_u32_u24_e32 v21, 0x90, v91
	s_waitcnt lgkmcnt(0)
	s_barrier
; #define LAS __attribute__((address_space(3)))
; __device__ __forceinline__ float fexp(float x) { return __builtin_amdgcn_exp2f(x * LOG2E); }
; __device__ __forceinline__ float sigm(float x) { return frcp(1.f + fexp(-x)); }
; __device__ __forceinline__ f32x4 mfma16(bf16x8 a, bf16x8 b, f32x4 c) { return __builtin_amdgcn_mfma_f32_16x16x32_bf16(a, b, c, 0, 0, 0); }
; __device__ __forceinline__ void lru_item(const Params& p, int l, int item, LAS unsigned char* lds) {
;     ...
;     { const bf16x8 a0 = *(const LAS bf16x8*)(xa + fr * 72 + fq * 8), a1 = *(const LAS bf16x8*)(xa + fr * 72 + 32 + fq * 8);
; #pragma unroll
;       for (int jt = 0; jt < 4; ++jt) {
;           f32x4 pa = mfma16(a0, wa0[jt], ZERO4); pa = mfma16(a1, wa1[jt], pa);
;           f32x4 px = mfma16(a0, wx0[jt], ZERO4); px = mfma16(a1, wx1[jt], px);
;           const int cj = l * 256 + h * 64 + jt * 16 + fr; const float bav = p.ba[cj], bxv = p.bx[cj], sp = p.spl[cj];
; #pragma unroll
;           for (int jj = 0; jj < 4; ++jj) { const int t = fq * 4 + jj; const float r = sigm(pa[jj] + bav), ig = sigm(px[jj] + bxv); const float la = -8.f * r * sp;
;               const float a = fexp(la); float mult = sqrtf(fmaxf(1.f - fexp(2.f * la), 0.f)); if (t0 + t == 0) mult = 1.f;
;               const int li = t * 66 + jt * 16 + fr; const float xcv = xf[li]; sa[li] = a; xf[li] = mult * ig * xcv; }
	v_add3_u32 v24, v79, v21, v20
	ds_read_b128 v[20:23], v24
	ds_read_b128 v[24:27], v24 offset:64
	s_waitcnt lgkmcnt(1)
	v_mfma_f32_16x16x32_bf16 v[60:63], v[20:23], v[60:63], 0
	v_or_b32_e32 v86, s4, v91
	v_ashrrev_i32_e32 v87, 31, v86
	s_waitcnt lgkmcnt(0)
	v_mfma_f32_16x16x32_bf16 v[82:85], v[24:27], v[64:67], v[60:63]
	v_mfma_f32_16x16x32_bf16 v[60:63], v[20:23], v[68:71], 0
	v_mfma_f32_16x16x32_bf16 v[70:73], v[24:27], v[72:75], v[60:63]
	v_mfma_f32_16x16x32_bf16 v[44:47], v[20:23], v[44:47], 0
	s_nop 5
	v_lshlrev_b64 v[60:61], 2, v[86:87]
	v_lshl_add_u64 v[64:65], s[30:31], 0, v[60:61]
	v_lshl_add_u64 v[62:63], s[6:7], 0, v[60:61]
	v_lshl_add_u64 v[60:61], s[34:35], 0, v[60:61]
	v_mfma_f32_16x16x32_bf16 v[48:51], v[24:27], v[48:51], v[44:47]
	s_waitcnt vmcnt(0)
	v_mov_b32_e32 v81, v156
	v_mov_b32_e32 v86, v157
	v_mov_b32_e32 v87, v158
	v_add_f32_e32 v66, v82, v81
	v_mul_f32_e32 v66, 0xbfb8aa3b, v66
	v_exp_f32_e32 v66, v66
	s_waitcnt vmcnt(1)
	v_add_f32_e32 v67, v70, v86
	v_mul_f32_e32 v67, 0xbfb8aa3b, v67
	v_exp_f32_e32 v67, v67
	v_add_f32_e32 v66, 1.0, v66
	v_rcp_f32_e32 v66, v66
	v_mfma_f32_16x16x32_bf16 v[44:47], v[20:23], v[52:55], 0
	v_add_f32_e32 v67, 1.0, v67
	v_rcp_f32_e32 v68, v67
	v_mul_f32_e32 v66, 0xc1000000, v66
	s_waitcnt vmcnt(0)
	v_mul_f32_e32 v66, v87, v66
	v_mul_f32_e32 v67, 0x3fb8aa3b, v66
	v_add_f32_e32 v66, v66, v66
	v_mul_f32_e32 v66, 0x3fb8aa3b, v66
	v_exp_f32_e32 v66, v66
	v_exp_f32_e32 v69, v67
	v_mfma_f32_16x16x32_bf16 v[44:47], v[24:27], v[56:59], v[44:47]
	v_sub_f32_e32 v66, 1.0, v66
	v_max_f32_e32 v66, 0, v66
	v_cmp_gt_f32_e32 vcc, s16, v66
	v_mul_f32_e32 v67, 0x4f800000, v66
	v_mfma_f32_16x16x32_bf16 v[28:31], v[20:23], v[28:31], 0
	v_cndmask_b32_e32 v66, v66, v67, vcc
	v_sqrt_f32_e32 v67, v66
	v_mfma_f32_16x16x32_bf16 v[32:35], v[24:27], v[32:35], v[28:31]
	v_add_u32_e32 v70, -1, v67
	v_fma_f32 v74, -v70, v67, v66
	v_cmp_ge_f32_e64 s[4:5], 0, v74
	v_add_u32_e32 v74, 1, v67
	v_mfma_f32_16x16x32_bf16 v[28:31], v[20:23], v[36:39], 0
	v_cndmask_b32_e64 v70, v67, v70, s[4:5]
	v_fma_f32 v67, -v74, v67, v66
	v_cmp_lt_f32_e64 s[4:5], 0, v67
	v_mfma_f32_16x16x32_bf16 v[28:31], v[24:27], v[40:43], v[28:31]
	s_nop 0
	v_cndmask_b32_e64 v67, v70, v74, s[4:5]
	v_mul_f32_e32 v70, 0x37800000, v67
	v_cndmask_b32_e32 v67, v67, v70, vcc
	v_cmp_class_f32_e32 vcc, v66, v205
	s_movk_i32 s4, 0x108
	v_mfma_f32_16x16x32_bf16 v[4:7], v[20:23], v[4:7], 0
	v_cndmask_b32_e32 v66, v67, v66, vcc
	v_or_b32_e32 v67, v76, v92
	v_cmp_eq_u32_e32 vcc, 0, v67
	v_mfma_f32_16x16x32_bf16 v[8:11], v[24:27], v[8:11], v[4:7]
	s_nop 0
	v_cndmask_b32_e64 v70, v66, 1.0, vcc
	v_mad_u32_u24 v66, v92, s4, v91
	v_lshl_add_u32 v74, v66, 2, v79
	v_add_u32_e32 v75, 0x800, v74
	ds_read2_b32 v[66:67], v75 offset0:64 offset1:80
	v_mul_f32_e32 v68, v68, v70
	ds_write_b32 v74, v69 offset:6528
	v_mfma_f32_16x16x32_bf16 v[4:7], v[20:23], v[12:15], 0
	s_waitcnt lgkmcnt(1)
	v_mul_f32_e32 v66, v66, v68
	ds_write_b32 v74, v66 offset:2304
	v_add_f32_e32 v66, v83, v81
	v_mul_f32_e32 v66, 0xbfb8aa3b, v66
	v_exp_f32_e32 v66, v66
	v_add_f32_e32 v68, v71, v86
	v_mul_f32_e32 v68, 0xbfb8aa3b, v68
	v_exp_f32_e32 v68, v68
	v_add_f32_e32 v66, 1.0, v66
	v_rcp_f32_e32 v66, v66
	v_mfma_f32_16x16x32_bf16 v[4:7], v[24:27], v[16:19], v[4:7]
	v_add_f32_e32 v68, 1.0, v68
	v_rcp_f32_e32 v70, v68
	v_mul_f32_e32 v66, 0xc1000000, v66
	v_mul_f32_e32 v66, v87, v66
	v_mul_f32_e32 v68, 0x3fb8aa3b, v66
	v_add_f32_e32 v66, v66, v66
	v_mul_f32_e32 v66, 0x3fb8aa3b, v66
	v_exp_f32_e32 v66, v66
	v_exp_f32_e32 v71, v68
	v_sub_f32_e32 v66, 1.0, v66
	v_max_f32_e32 v66, 0, v66
	v_cmp_gt_f32_e64 s[4:5], s16, v66
	v_mul_f32_e32 v68, 0x4f800000, v66
	s_nop 0
	v_cndmask_b32_e64 v66, v66, v68, s[4:5]
	v_sqrt_f32_e32 v68, v66
	s_nop 0
	v_add_u32_e32 v69, -1, v68
	v_fma_f32 v76, -v69, v68, v66
	v_cmp_ge_f32_e64 s[6:7], 0, v76
	v_add_u32_e32 v76, 1, v68
	s_nop 0
	v_cndmask_b32_e64 v69, v68, v69, s[6:7]
	v_fma_f32 v68, -v76, v68, v66
	v_cmp_lt_f32_e64 s[6:7], 0, v68
	s_nop 1
	v_cndmask_b32_e64 v68, v69, v76, s[6:7]
	v_mul_f32_e32 v69, 0x37800000, v68
	v_cndmask_b32_e64 v68, v68, v69, s[4:5]
	v_cmp_class_f32_e64 s[4:5], v66, v205
	s_nop 1
	v_cndmask_b32_e64 v66, v68, v66, s[4:5]
	ds_read2_b32 v[68:69], v75 offset0:130 offset1:146
	v_mul_f32_e32 v66, v70, v66
	ds_write_b32 v74, v71 offset:6792
	s_waitcnt lgkmcnt(1)
	v_mul_f32_e32 v66, v68, v66
	ds_write_b32 v74, v66 offset:2568
	v_add_f32_e32 v66, v84, v81
	v_mul_f32_e32 v66, 0xbfb8aa3b, v66
	v_exp_f32_e32 v66, v66
	v_add_f32_e32 v68, v72, v86
	v_mul_f32_e32 v68, 0xbfb8aa3b, v68
	v_exp_f32_e32 v68, v68
	v_add_f32_e32 v66, 1.0, v66
	v_rcp_f32_e32 v66, v66
	v_add_f32_e32 v68, 1.0, v68
	v_rcp_f32_e32 v68, v68
	v_mul_f32_e32 v66, 0xc1000000, v66
	v_mul_f32_e32 v66, v87, v66
	v_mul_f32_e32 v70, 0x3fb8aa3b, v66
	v_add_f32_e32 v66, v66, v66
	v_mul_f32_e32 v66, 0x3fb8aa3b, v66
	v_exp_f32_e32 v66, v66
	v_exp_f32_e32 v72, v70
	v_sub_f32_e32 v66, 1.0, v66
	v_max_f32_e32 v66, 0, v66
	v_cmp_gt_f32_e64 s[4:5], s16, v66
	v_mul_f32_e32 v70, 0x4f800000, v66
	s_nop 0
	v_cndmask_b32_e64 v66, v66, v70, s[4:5]
	v_sqrt_f32_e32 v70, v66
	s_nop 0
	v_add_u32_e32 v71, -1, v70
	v_fma_f32 v76, -v71, v70, v66
	v_cmp_ge_f32_e64 s[6:7], 0, v76
	v_add_u32_e32 v76, 1, v70
	s_nop 0
	v_cndmask_b32_e64 v71, v70, v71, s[6:7]
	v_fma_f32 v70, -v76, v70, v66
	v_cmp_lt_f32_e64 s[6:7], 0, v70
	s_nop 1
	v_cndmask_b32_e64 v70, v71, v76, s[6:7]
	v_mul_f32_e32 v71, 0x37800000, v70
	v_cndmask_b32_e64 v70, v70, v71, s[4:5]
	v_cmp_class_f32_e64 s[4:5], v66, v205
	s_nop 1
	v_cndmask_b32_e64 v66, v70, v66, s[4:5]
	ds_read2_b32 v[70:71], v75 offset0:196 offset1:212
	v_mul_f32_e32 v66, v68, v66
	v_add_f32_e32 v68, v73, v86
	v_mul_f32_e32 v68, 0xbfb8aa3b, v68
	v_exp_f32_e32 v68, v68
	s_waitcnt lgkmcnt(0)
; __device__ __forceinline__ float fexp(float x) { return __builtin_amdgcn_exp2f(x * LOG2E); }
; __device__ __forceinline__ float sigm(float x) { return frcp(1.f + fexp(-x)); }
; __device__ __forceinline__ void lru_item(const Params& p, int l, int item, LAS unsigned char* lds) {
;     ...
;           const int cj = l * 256 + h * 64 + jt * 16 + fr; const float bav = p.ba[cj], bxv = p.bx[cj], sp = p.spl[cj];
; #pragma unroll
;           for (int jj = 0; jj < 4; ++jj) { const int t = fq * 4 + jj; const float r = sigm(pa[jj] + bav), ig = sigm(px[jj] + bxv); const float la = -8.f * r * sp;
;               const float a = fexp(la); float mult = sqrtf(fmaxf(1.f - fexp(2.f * la), 0.f)); if (t0 + t == 0) mult = 1.f;
;               const int li = t * 66 + jt * 16 + fr; const float xcv = xf[li]; sa[li] = a; xf[li] = mult * ig * xcv; }
	v_mul_f32_e32 v66, v70, v66
	ds_write_b32 v74, v66 offset:2832
	v_add_f32_e32 v66, v85, v81
	v_mul_f32_e32 v66, 0xbfb8aa3b, v66
	v_exp_f32_e32 v66, v66
	v_add_f32_e32 v68, 1.0, v68
	v_rcp_f32_e32 v70, v68
	ds_write_b32 v74, v72 offset:7056
	v_add_f32_e32 v66, 1.0, v66
	v_rcp_f32_e32 v66, v66
	s_nop 0
	v_mul_f32_e32 v66, 0xc1000000, v66
	v_mul_f32_e32 v66, v87, v66
	v_mul_f32_e32 v68, 0x3fb8aa3b, v66
	v_add_f32_e32 v66, v66, v66
	v_mul_f32_e32 v66, 0x3fb8aa3b, v66
	v_exp_f32_e32 v66, v66
	v_exp_f32_e32 v68, v68
	v_sub_f32_e32 v66, 1.0, v66
	v_max_f32_e32 v66, 0, v66
	v_cmp_gt_f32_e64 s[4:5], s16, v66
	v_mul_f32_e32 v72, 0x4f800000, v66
	s_nop 0
	v_cndmask_b32_e64 v66, v66, v72, s[4:5]
	v_sqrt_f32_e32 v72, v66
	s_nop 0
	v_add_u32_e32 v73, -1, v72
	v_fma_f32 v76, -v73, v72, v66
	v_cmp_ge_f32_e64 s[6:7], 0, v76
	v_add_u32_e32 v76, 1, v72
	s_nop 0
	v_cndmask_b32_e64 v73, v72, v73, s[6:7]
	v_fma_f32 v72, -v76, v72, v66
	v_cmp_lt_f32_e64 s[6:7], 0, v72
	s_nop 1
	v_cndmask_b32_e64 v72, v73, v76, s[6:7]
	v_mul_f32_e32 v73, 0x37800000, v72
	v_cndmask_b32_e64 v72, v72, v73, s[4:5]
	v_cmp_class_f32_e64 s[4:5], v66, v205
	s_nop 1
	v_cndmask_b32_e64 v76, v72, v66, s[4:5]
	v_add_u32_e32 v66, 0xc00, v74
	ds_read2_b32 v[72:73], v66 offset0:6 offset1:22
	v_mov_b32_e32 v52, v159
	v_mov_b32_e32 v53, v160
	v_mov_b32_e32 v54, v161
	v_mul_f32_e32 v70, v70, v76
	s_waitcnt lgkmcnt(0)
	v_mul_f32_e32 v70, v72, v70
	s_waitcnt vmcnt(2)
	v_add_f32_e32 v48, v48, v52
	v_mul_f32_e32 v48, 0xbfb8aa3b, v48
	v_exp_f32_e32 v48, v48
	s_waitcnt vmcnt(1)
	v_add_f32_e32 v44, v44, v53
	v_mul_f32_e32 v44, 0xbfb8aa3b, v44
	v_exp_f32_e32 v44, v44
	v_add_f32_e32 v48, 1.0, v48
	v_rcp_f32_e32 v48, v48
	v_add_f32_e32 v45, v45, v53
	v_add_f32_e32 v44, 1.0, v44
	v_rcp_f32_e32 v44, v44
	v_mul_f32_e32 v48, 0xc1000000, v48
	s_waitcnt vmcnt(0)
	v_mul_f32_e32 v48, v54, v48
	v_mul_f32_e32 v55, 0x3fb8aa3b, v48
	v_add_f32_e32 v48, v48, v48
	v_mul_f32_e32 v48, 0x3fb8aa3b, v48
	v_exp_f32_e32 v48, v48
	v_exp_f32_e32 v55, v55
	v_mul_f32_e32 v45, 0xbfb8aa3b, v45
	v_exp_f32_e32 v45, v45
	v_sub_f32_e32 v48, 1.0, v48
	v_max_f32_e32 v48, 0, v48
	v_cmp_gt_f32_e64 s[4:5], s16, v48
	v_mul_f32_e32 v56, 0x4f800000, v48
	ds_write_b32 v74, v55 offset:6592
	v_cndmask_b32_e64 v48, v48, v56, s[4:5]
	v_sqrt_f32_e32 v56, v48
	v_add_f32_e32 v45, 1.0, v45
	v_rcp_f32_e32 v45, v45
	v_add_u32_e32 v57, -1, v56
	v_fma_f32 v58, -v57, v56, v48
	v_cmp_ge_f32_e64 s[6:7], 0, v58
	v_add_u32_e32 v58, 1, v56
	s_nop 0
	v_cndmask_b32_e64 v57, v56, v57, s[6:7]
	v_fma_f32 v56, -v58, v56, v48
	v_cmp_lt_f32_e64 s[6:7], 0, v56
	s_nop 1
	v_cndmask_b32_e64 v56, v57, v58, s[6:7]
	v_mul_f32_e32 v57, 0x37800000, v56
	v_cndmask_b32_e64 v56, v56, v57, s[4:5]
	v_cmp_class_f32_e64 s[4:5], v48, v205
	s_nop 1
	v_cndmask_b32_e64 v48, v56, v48, s[4:5]
	v_cndmask_b32_e64 v48, v48, 1.0, vcc
	v_mul_f32_e32 v44, v44, v48
	v_mul_f32_e32 v48, v67, v44
	v_add_f32_e32 v44, v49, v52
	v_mul_f32_e32 v44, 0xbfb8aa3b, v44
	v_exp_f32_e32 v44, v44
	s_nop 0
	v_add_f32_e32 v44, 1.0, v44
	v_rcp_f32_e32 v44, v44
	s_nop 0
	v_mul_f32_e32 v44, 0xc1000000, v44
	v_mul_f32_e32 v44, v54, v44
	v_mul_f32_e32 v49, 0x3fb8aa3b, v44
	v_add_f32_e32 v44, v44, v44
	v_mul_f32_e32 v44, 0x3fb8aa3b, v44
	v_exp_f32_e32 v44, v44
	v_exp_f32_e32 v49, v49
	v_sub_f32_e32 v44, 1.0, v44
	v_max_f32_e32 v44, 0, v44
	v_cmp_gt_f32_e64 s[4:5], s16, v44
	v_mul_f32_e32 v55, 0x4f800000, v44
	ds_write_b32 v74, v49 offset:6856
	v_cndmask_b32_e64 v44, v44, v55, s[4:5]
	v_sqrt_f32_e32 v55, v44
	s_nop 0
	v_add_u32_e32 v56, -1, v55
	v_fma_f32 v57, -v56, v55, v44
	v_cmp_ge_f32_e64 s[6:7], 0, v57
	v_add_u32_e32 v57, 1, v55
	s_nop 0
	v_cndmask_b32_e64 v56, v55, v56, s[6:7]
	v_fma_f32 v55, -v57, v55, v44
	v_cmp_lt_f32_e64 s[6:7], 0, v55
	s_nop 1
	v_cndmask_b32_e64 v55, v56, v57, s[6:7]
	v_mul_f32_e32 v56, 0x37800000, v55
	v_cndmask_b32_e64 v55, v55, v56, s[4:5]
	v_cmp_class_f32_e64 s[4:5], v44, v205
	s_nop 1
	v_cndmask_b32_e64 v44, v55, v44, s[4:5]
	v_mul_f32_e32 v44, v45, v44
	v_mul_f32_e32 v44, v69, v44
	ds_write_b32 v74, v44 offset:2632
	v_add_f32_e32 v44, v50, v52
	v_mul_f32_e32 v44, 0xbfb8aa3b, v44
	v_exp_f32_e32 v44, v44
	v_add_f32_e32 v45, v46, v53
	v_mul_f32_e32 v45, 0xbfb8aa3b, v45
	v_exp_f32_e32 v45, v45
	v_add_f32_e32 v44, 1.0, v44
	v_rcp_f32_e32 v44, v44
	v_add_f32_e32 v45, 1.0, v45
	v_rcp_f32_e32 v45, v45
	v_mul_f32_e32 v44, 0xc1000000, v44
	v_mul_f32_e32 v44, v54, v44
	v_mul_f32_e32 v46, 0x3fb8aa3b, v44
	v_add_f32_e32 v44, v44, v44
	v_mul_f32_e32 v44, 0x3fb8aa3b, v44
	v_exp_f32_e32 v44, v44
	v_exp_f32_e32 v46, v46
	v_sub_f32_e32 v44, 1.0, v44
	v_max_f32_e32 v44, 0, v44
	v_cmp_gt_f32_e64 s[4:5], s16, v44
	v_mul_f32_e32 v49, 0x4f800000, v44
	ds_write_b32 v74, v46 offset:7120
	v_cndmask_b32_e64 v44, v44, v49, s[4:5]
	v_sqrt_f32_e32 v49, v44
	s_nop 0
	v_add_u32_e32 v50, -1, v49
	v_fma_f32 v55, -v50, v49, v44
	v_cmp_ge_f32_e64 s[6:7], 0, v55
	v_add_u32_e32 v55, 1, v49
	s_nop 0
	v_cndmask_b32_e64 v50, v49, v50, s[6:7]
	v_fma_f32 v49, -v55, v49, v44
	v_cmp_lt_f32_e64 s[6:7], 0, v49
	s_nop 1
	v_cndmask_b32_e64 v49, v50, v55, s[6:7]
	v_mul_f32_e32 v50, 0x37800000, v49
	v_cndmask_b32_e64 v49, v49, v50, s[4:5]
	v_cmp_class_f32_e64 s[4:5], v44, v205
	s_nop 1
	v_cndmask_b32_e64 v44, v49, v44, s[4:5]
	v_mul_f32_e32 v44, v45, v44
	v_mul_f32_e32 v44, v71, v44
	ds_write_b32 v74, v44 offset:2896
	v_add_f32_e32 v44, v51, v52
	v_mul_f32_e32 v44, 0xbfb8aa3b, v44
	v_exp_f32_e32 v44, v44
	v_add_f32_e32 v45, v47, v53
	v_mul_f32_e32 v45, 0xbfb8aa3b, v45
	v_exp_f32_e32 v45, v45
	v_add_f32_e32 v44, 1.0, v44
	v_rcp_f32_e32 v44, v44
	v_add_f32_e32 v45, 1.0, v45
	v_rcp_f32_e32 v45, v45
	v_mul_f32_e32 v44, 0xc1000000, v44
	v_mul_f32_e32 v44, v54, v44
	v_mul_f32_e32 v46, 0x3fb8aa3b, v44
	v_add_f32_e32 v44, v44, v44
	v_mul_f32_e32 v44, 0x3fb8aa3b, v44
	v_exp_f32_e32 v44, v44
	v_exp_f32_e32 v46, v46
	v_sub_f32_e32 v44, 1.0, v44
	v_max_f32_e32 v44, 0, v44
	v_cmp_gt_f32_e64 s[4:5], s16, v44
	v_mul_f32_e32 v47, 0x4f800000, v44
	s_nop 0
	v_cndmask_b32_e64 v44, v44, v47, s[4:5]
	v_sqrt_f32_e32 v47, v44
	s_nop 0
	v_add_u32_e32 v49, -1, v47
	v_fma_f32 v50, -v49, v47, v44
	v_cmp_ge_f32_e64 s[6:7], 0, v50
	v_add_u32_e32 v50, 1, v47
	s_nop 0
	v_cndmask_b32_e64 v49, v47, v49, s[6:7]
	v_fma_f32 v47, -v50, v47, v44
	v_cmp_lt_f32_e64 s[6:7], 0, v47
	s_nop 1
	v_cndmask_b32_e64 v47, v49, v50, s[6:7]
	v_mul_f32_e32 v49, 0x37800000, v47
	v_cndmask_b32_e64 v47, v47, v49, s[4:5]
	v_cmp_class_f32_e64 s[4:5], v44, v205
	s_nop 1
	v_cndmask_b32_e64 v47, v47, v44, s[4:5]
	v_mul_f32_e32 v45, v45, v47
	v_add_u32_e32 v44, 0x1c00, v74
	v_mul_f32_e32 v45, v73, v45
	ds_write2_b32 v44, v68, v46 offset0:38 offset1:54
	ds_write2_b32 v66, v70, v45 offset0:6 offset1:22
	v_mov_b32_e32 v40, v162
	v_mov_b32_e32 v41, v163
	v_mov_b32_e32 v42, v164
	s_waitcnt vmcnt(2)
; __device__ __forceinline__ float fexp(float x) { return __builtin_amdgcn_exp2f(x * LOG2E); }
; __device__ __forceinline__ float sigm(float x) { return frcp(1.f + fexp(-x)); }
; __device__ __forceinline__ void lru_item(const Params& p, int l, int item, LAS unsigned char* lds) {
;     ...
;           const int cj = l * 256 + h * 64 + jt * 16 + fr; const float bav = p.ba[cj], bxv = p.bx[cj], sp = p.spl[cj];
; #pragma unroll
;           for (int jj = 0; jj < 4; ++jj) { const int t = fq * 4 + jj; const float r = sigm(pa[jj] + bav), ig = sigm(px[jj] + bxv); const float la = -8.f * r * sp;
;               const float a = fexp(la); float mult = sqrtf(fmaxf(1.f - fexp(2.f * la), 0.f)); if (t0 + t == 0) mult = 1.f;
;               const int li = t * 66 + jt * 16 + fr; const float xcv = xf[li]; sa[li] = a; xf[li] = mult * ig * xcv; }
	v_add_f32_e32 v32, v32, v40
	v_mul_f32_e32 v32, 0xbfb8aa3b, v32
	v_exp_f32_e32 v32, v32
	s_waitcnt vmcnt(1)
	v_add_f32_e32 v28, v28, v41
	v_mul_f32_e32 v28, 0xbfb8aa3b, v28
	v_exp_f32_e32 v28, v28
	v_add_f32_e32 v32, 1.0, v32
	v_rcp_f32_e32 v32, v32
	v_add_f32_e32 v29, v29, v41
	v_add_f32_e32 v28, 1.0, v28
	v_rcp_f32_e32 v28, v28
	v_mul_f32_e32 v32, 0xc1000000, v32
	s_waitcnt vmcnt(0)
	v_mul_f32_e32 v32, v42, v32
	v_mul_f32_e32 v36, 0x3fb8aa3b, v32
	v_add_f32_e32 v32, v32, v32
	v_mul_f32_e32 v32, 0x3fb8aa3b, v32
	v_exp_f32_e32 v32, v32
	v_exp_f32_e32 v36, v36
	v_mul_f32_e32 v29, 0xbfb8aa3b, v29
	v_exp_f32_e32 v29, v29
	v_sub_f32_e32 v32, 1.0, v32
	v_max_f32_e32 v32, 0, v32
	v_cmp_gt_f32_e64 s[4:5], s16, v32
	v_mul_f32_e32 v37, 0x4f800000, v32
	ds_write_b32 v74, v36 offset:6656
	v_cndmask_b32_e64 v32, v32, v37, s[4:5]
	v_sqrt_f32_e32 v37, v32
	v_add_f32_e32 v29, 1.0, v29
	v_rcp_f32_e32 v29, v29
	v_add_u32_e32 v38, -1, v37
	v_fma_f32 v39, -v38, v37, v32
	v_cmp_ge_f32_e64 s[6:7], 0, v39
	v_add_u32_e32 v39, 1, v37
	s_nop 0
	v_cndmask_b32_e64 v38, v37, v38, s[6:7]
	v_fma_f32 v37, -v39, v37, v32
	v_cmp_lt_f32_e64 s[6:7], 0, v37
	s_nop 1
	v_cndmask_b32_e64 v37, v38, v39, s[6:7]
	v_mul_f32_e32 v38, 0x37800000, v37
	v_cndmask_b32_e64 v37, v37, v38, s[4:5]
	ds_read2_b32 v[38:39], v75 offset0:96 offset1:112
	v_cmp_class_f32_e64 s[4:5], v32, v205
	s_nop 1
	v_cndmask_b32_e64 v32, v37, v32, s[4:5]
	v_cndmask_b32_e64 v32, v32, 1.0, vcc
	v_mul_f32_e32 v28, v28, v32
	s_waitcnt lgkmcnt(0)
	v_mul_f32_e32 v28, v38, v28
	ds_write2_b32 v75, v48, v28 offset0:80 offset1:96
	v_add_f32_e32 v28, v33, v40
	v_mul_f32_e32 v28, 0xbfb8aa3b, v28
	v_exp_f32_e32 v28, v28
	s_nop 0
	v_add_f32_e32 v28, 1.0, v28
	v_rcp_f32_e32 v28, v28
	s_nop 0
	v_mul_f32_e32 v28, 0xc1000000, v28
	v_mul_f32_e32 v28, v42, v28
	v_mul_f32_e32 v32, 0x3fb8aa3b, v28
	v_add_f32_e32 v28, v28, v28
	v_mul_f32_e32 v28, 0x3fb8aa3b, v28
	v_exp_f32_e32 v28, v28
	v_exp_f32_e32 v32, v32
	v_sub_f32_e32 v28, 1.0, v28
	v_max_f32_e32 v28, 0, v28
	v_cmp_gt_f32_e64 s[4:5], s16, v28
	v_mul_f32_e32 v33, 0x4f800000, v28
	s_nop 0
	v_cndmask_b32_e64 v28, v28, v33, s[4:5]
	v_sqrt_f32_e32 v33, v28
	s_nop 0
	v_add_u32_e32 v36, -1, v33
	v_fma_f32 v37, -v36, v33, v28
	v_cmp_ge_f32_e64 s[6:7], 0, v37
	v_add_u32_e32 v37, 1, v33
	s_nop 0
	v_cndmask_b32_e64 v36, v33, v36, s[6:7]
	v_fma_f32 v33, -v37, v33, v28
	v_cmp_lt_f32_e64 s[6:7], 0, v33
	s_nop 1
	v_cndmask_b32_e64 v33, v36, v37, s[6:7]
	v_mul_f32_e32 v36, 0x37800000, v33
	v_cndmask_b32_e64 v33, v33, v36, s[4:5]
	ds_read2_b32 v[36:37], v75 offset0:162 offset1:178
	v_cmp_class_f32_e64 s[4:5], v28, v205
	ds_write_b32 v74, v32 offset:6920
	s_nop 0
	v_cndmask_b32_e64 v28, v33, v28, s[4:5]
	v_mul_f32_e32 v28, v29, v28
	s_waitcnt lgkmcnt(1)
	v_mul_f32_e32 v28, v36, v28
	ds_write_b32 v74, v28 offset:2696
	v_add_f32_e32 v28, v34, v40
	v_mul_f32_e32 v28, 0xbfb8aa3b, v28
	v_exp_f32_e32 v28, v28
	v_add_f32_e32 v29, v30, v41
	v_mul_f32_e32 v29, 0xbfb8aa3b, v29
	v_exp_f32_e32 v29, v29
	v_add_f32_e32 v28, 1.0, v28
	v_rcp_f32_e32 v28, v28
	v_add_f32_e32 v29, 1.0, v29
	v_rcp_f32_e32 v29, v29
	v_mul_f32_e32 v28, 0xc1000000, v28
	v_mul_f32_e32 v28, v42, v28
	v_mul_f32_e32 v30, 0x3fb8aa3b, v28
	v_add_f32_e32 v28, v28, v28
	v_mul_f32_e32 v28, 0x3fb8aa3b, v28
	v_exp_f32_e32 v28, v28
	v_exp_f32_e32 v30, v30
	v_sub_f32_e32 v28, 1.0, v28
	v_max_f32_e32 v28, 0, v28
	v_cmp_gt_f32_e64 s[4:5], s16, v28
	v_mul_f32_e32 v32, 0x4f800000, v28
	s_nop 0
	v_cndmask_b32_e64 v28, v28, v32, s[4:5]
	v_sqrt_f32_e32 v32, v28
	s_nop 0
	v_add_u32_e32 v33, -1, v32
	v_fma_f32 v34, -v33, v32, v28
	v_cmp_ge_f32_e64 s[6:7], 0, v34
	v_add_u32_e32 v34, 1, v32
	s_nop 0
	v_cndmask_b32_e64 v33, v32, v33, s[6:7]
	v_fma_f32 v32, -v34, v32, v28
	v_cmp_lt_f32_e64 s[6:7], 0, v32
	s_nop 1
	v_cndmask_b32_e64 v32, v33, v34, s[6:7]
	v_mul_f32_e32 v33, 0x37800000, v32
	v_cndmask_b32_e64 v32, v32, v33, s[4:5]
	v_cmp_class_f32_e64 s[4:5], v28, v205
	s_nop 1
	v_cndmask_b32_e64 v28, v32, v28, s[4:5]
	ds_read2_b32 v[32:33], v75 offset0:228 offset1:244
	v_mul_f32_e32 v28, v29, v28
	v_add_f32_e32 v29, v31, v41
	v_mul_f32_e32 v29, 0xbfb8aa3b, v29
	v_exp_f32_e32 v29, v29
	s_waitcnt lgkmcnt(0)
	v_mul_f32_e32 v28, v32, v28
	ds_write_b32 v74, v28 offset:2960
	v_add_f32_e32 v28, v35, v40
	v_mul_f32_e32 v28, 0xbfb8aa3b, v28
	v_exp_f32_e32 v28, v28
	v_add_f32_e32 v29, 1.0, v29
	v_rcp_f32_e32 v31, v29
	ds_write_b32 v74, v30 offset:7184
	v_add_f32_e32 v28, 1.0, v28
	v_rcp_f32_e32 v28, v28
	s_nop 0
	v_mul_f32_e32 v28, 0xc1000000, v28
	v_mul_f32_e32 v28, v42, v28
	v_mul_f32_e32 v29, 0x3fb8aa3b, v28
	v_add_f32_e32 v28, v28, v28
	v_mul_f32_e32 v28, 0x3fb8aa3b, v28
	v_exp_f32_e32 v28, v28
	v_exp_f32_e32 v30, v29
	v_sub_f32_e32 v28, 1.0, v28
	v_max_f32_e32 v28, 0, v28
	v_cmp_gt_f32_e64 s[4:5], s16, v28
	v_mul_f32_e32 v29, 0x4f800000, v28
	s_nop 0
	v_cndmask_b32_e64 v28, v28, v29, s[4:5]
	v_sqrt_f32_e32 v29, v28
	s_nop 0
	v_add_u32_e32 v32, -1, v29
	v_fma_f32 v34, -v32, v29, v28
	v_cmp_ge_f32_e64 s[6:7], 0, v34
	v_add_u32_e32 v34, 1, v29
	s_nop 0
	v_cndmask_b32_e64 v32, v29, v32, s[6:7]
	v_fma_f32 v29, -v34, v29, v28
	v_cmp_lt_f32_e64 s[6:7], 0, v29
	s_nop 1
	v_cndmask_b32_e64 v29, v32, v34, s[6:7]
	v_mul_f32_e32 v32, 0x37800000, v29
	v_cndmask_b32_e64 v29, v29, v32, s[4:5]
	v_cmp_class_f32_e64 s[4:5], v28, v205
	s_nop 1
	v_cndmask_b32_e64 v32, v29, v28, s[4:5]
	ds_read2_b32 v[28:29], v66 offset0:38 offset1:54
	v_mov_b32_e32 v12, v165
	v_mov_b32_e32 v13, v166
	v_mov_b32_e32 v14, v167
	v_mul_f32_e32 v31, v31, v32
	s_waitcnt lgkmcnt(0)
	v_mul_f32_e32 v28, v28, v31
	s_waitcnt vmcnt(2)
	v_add_f32_e32 v8, v8, v12
	v_mul_f32_e32 v8, 0xbfb8aa3b, v8
	v_exp_f32_e32 v8, v8
	s_waitcnt vmcnt(1)
; __device__ __forceinline__ float fexp(float x) { return __builtin_amdgcn_exp2f(x * LOG2E); }
; __device__ __forceinline__ float sigm(float x) { return frcp(1.f + fexp(-x)); }
; __device__ __forceinline__ void lds_barrier() { asm volatile("s_waitcnt lgkmcnt(0)" ::: "memory"); __builtin_amdgcn_s_barrier(); asm volatile("" ::: "memory"); }
; __device__ __forceinline__ void lru_item(const Params& p, int l, int item, LAS unsigned char* lds) {
;     ...
;           for (int jj = 0; jj < 4; ++jj) { const int t = fq * 4 + jj; const float r = sigm(pa[jj] + bav), ig = sigm(px[jj] + bxv); const float la = -8.f * r * sp;
;               const float a = fexp(la); float mult = sqrtf(fmaxf(1.f - fexp(2.f * la), 0.f)); if (t0 + t == 0) mult = 1.f;
;               const int li = t * 66 + jt * 16 + fr; const float xcv = xf[li]; sa[li] = a; xf[li] = mult * ig * xcv; }
;       } }
;     lds_barrier();
	v_add_f32_e32 v4, v4, v13
	v_mul_f32_e32 v4, 0xbfb8aa3b, v4
	v_exp_f32_e32 v4, v4
	v_add_f32_e32 v8, 1.0, v8
	v_rcp_f32_e32 v8, v8
	v_add_f32_e32 v5, v5, v13
	v_add_f32_e32 v4, 1.0, v4
	v_rcp_f32_e32 v4, v4
	v_mul_f32_e32 v8, 0xc1000000, v8
	s_waitcnt vmcnt(0)
	v_mul_f32_e32 v8, v14, v8
	v_mul_f32_e32 v15, 0x3fb8aa3b, v8
	v_add_f32_e32 v8, v8, v8
	v_mul_f32_e32 v8, 0x3fb8aa3b, v8
	v_exp_f32_e32 v8, v8
	v_exp_f32_e32 v15, v15
	v_mul_f32_e32 v5, 0xbfb8aa3b, v5
	v_exp_f32_e32 v5, v5
	v_sub_f32_e32 v8, 1.0, v8
	v_max_f32_e32 v8, 0, v8
	v_cmp_gt_f32_e64 s[4:5], s16, v8
	v_mul_f32_e32 v16, 0x4f800000, v8
	ds_write_b32 v74, v15 offset:6720
	v_cndmask_b32_e64 v8, v8, v16, s[4:5]
	v_sqrt_f32_e32 v16, v8
	v_add_f32_e32 v5, 1.0, v5
	v_rcp_f32_e32 v5, v5
	v_add_u32_e32 v17, -1, v16
	v_fma_f32 v18, -v17, v16, v8
	v_cmp_ge_f32_e64 s[6:7], 0, v18
	v_add_u32_e32 v18, 1, v16
	s_nop 0
	v_cndmask_b32_e64 v17, v16, v17, s[6:7]
	v_fma_f32 v16, -v18, v16, v8
	v_cmp_lt_f32_e64 s[6:7], 0, v16
	s_nop 1
	v_cndmask_b32_e64 v16, v17, v18, s[6:7]
	v_mul_f32_e32 v17, 0x37800000, v16
	v_cndmask_b32_e64 v16, v16, v17, s[4:5]
	v_cmp_class_f32_e64 s[4:5], v8, v205
	s_nop 1
	v_cndmask_b32_e64 v8, v16, v8, s[4:5]
	v_cndmask_b32_e64 v8, v8, 1.0, vcc
	v_mul_f32_e32 v4, v4, v8
	v_mul_f32_e32 v4, v39, v4
	ds_write_b32 v74, v4 offset:2496
	v_add_f32_e32 v4, v9, v12
	v_mul_f32_e32 v4, 0xbfb8aa3b, v4
	v_exp_f32_e32 v4, v4
	s_nop 0
	v_add_f32_e32 v4, 1.0, v4
	v_rcp_f32_e32 v4, v4
	s_nop 0
	v_mul_f32_e32 v4, 0xc1000000, v4
	v_mul_f32_e32 v4, v14, v4
	v_mul_f32_e32 v8, 0x3fb8aa3b, v4
	v_add_f32_e32 v4, v4, v4
	v_mul_f32_e32 v4, 0x3fb8aa3b, v4
	v_exp_f32_e32 v4, v4
	v_exp_f32_e32 v8, v8
	v_sub_f32_e32 v4, 1.0, v4
	v_max_f32_e32 v4, 0, v4
	v_cmp_gt_f32_e32 vcc, s16, v4
	v_mul_f32_e32 v9, 0x4f800000, v4
	ds_write_b32 v74, v8 offset:6984
	v_cndmask_b32_e32 v4, v4, v9, vcc
	v_sqrt_f32_e32 v9, v4
	s_nop 0
	v_add_u32_e32 v15, -1, v9
	v_fma_f32 v16, -v15, v9, v4
	v_cmp_ge_f32_e64 s[4:5], 0, v16
	v_add_u32_e32 v16, 1, v9
	s_nop 0
	v_cndmask_b32_e64 v15, v9, v15, s[4:5]
	v_fma_f32 v9, -v16, v9, v4
	v_cmp_lt_f32_e64 s[4:5], 0, v9
	s_nop 1
	v_cndmask_b32_e64 v9, v15, v16, s[4:5]
	v_mul_f32_e32 v15, 0x37800000, v9
	v_cndmask_b32_e32 v9, v9, v15, vcc
	v_cmp_class_f32_e32 vcc, v4, v205
	s_nop 1
	v_cndmask_b32_e32 v4, v9, v4, vcc
	v_mul_f32_e32 v4, v5, v4
	v_mul_f32_e32 v4, v37, v4
	ds_write_b32 v74, v4 offset:2760
	v_add_f32_e32 v4, v10, v12
	v_mul_f32_e32 v4, 0xbfb8aa3b, v4
	v_exp_f32_e32 v4, v4
	v_add_f32_e32 v5, v6, v13
	v_mul_f32_e32 v5, 0xbfb8aa3b, v5
	v_exp_f32_e32 v5, v5
	v_add_f32_e32 v4, 1.0, v4
	v_rcp_f32_e32 v4, v4
	v_add_f32_e32 v5, 1.0, v5
	v_rcp_f32_e32 v5, v5
	v_mul_f32_e32 v4, 0xc1000000, v4
	v_mul_f32_e32 v4, v14, v4
	v_mul_f32_e32 v6, 0x3fb8aa3b, v4
	v_add_f32_e32 v4, v4, v4
	v_mul_f32_e32 v4, 0x3fb8aa3b, v4
	v_exp_f32_e32 v4, v4
	v_exp_f32_e32 v6, v6
	v_sub_f32_e32 v4, 1.0, v4
	v_max_f32_e32 v4, 0, v4
	v_cmp_gt_f32_e32 vcc, s16, v4
	v_mul_f32_e32 v8, 0x4f800000, v4
	ds_write_b32 v74, v6 offset:7248
	v_cndmask_b32_e32 v4, v4, v8, vcc
	v_sqrt_f32_e32 v8, v4
	s_nop 0
	v_add_u32_e32 v9, -1, v8
	v_fma_f32 v10, -v9, v8, v4
	v_cmp_ge_f32_e64 s[4:5], 0, v10
	v_add_u32_e32 v10, 1, v8
	s_nop 0
	v_cndmask_b32_e64 v9, v8, v9, s[4:5]
	v_fma_f32 v8, -v10, v8, v4
	v_cmp_lt_f32_e64 s[4:5], 0, v8
	s_nop 1
	v_cndmask_b32_e64 v8, v9, v10, s[4:5]
	v_mul_f32_e32 v9, 0x37800000, v8
	v_cndmask_b32_e32 v8, v8, v9, vcc
	v_cmp_class_f32_e32 vcc, v4, v205
	s_nop 1
	v_cndmask_b32_e32 v4, v8, v4, vcc
	v_mul_f32_e32 v4, v5, v4
	v_mul_f32_e32 v4, v33, v4
	ds_write_b32 v74, v4 offset:3024
	v_add_f32_e32 v4, v11, v12
	v_mul_f32_e32 v4, 0xbfb8aa3b, v4
	v_exp_f32_e32 v4, v4
	v_add_f32_e32 v5, v7, v13
	v_mul_f32_e32 v5, 0xbfb8aa3b, v5
	v_exp_f32_e32 v5, v5
	v_add_f32_e32 v4, 1.0, v4
	v_rcp_f32_e32 v4, v4
	v_add_f32_e32 v5, 1.0, v5
	v_rcp_f32_e32 v5, v5
	v_mul_f32_e32 v4, 0xc1000000, v4
	v_mul_f32_e32 v4, v14, v4
	v_mul_f32_e32 v6, 0x3fb8aa3b, v4
	v_add_f32_e32 v4, v4, v4
	v_mul_f32_e32 v4, 0x3fb8aa3b, v4
	v_exp_f32_e32 v4, v4
	v_exp_f32_e32 v6, v6
	v_lshl_add_u32 v14, v3, 2, v79
	v_sub_f32_e32 v4, 1.0, v4
	v_max_f32_e32 v4, 0, v4
	v_cmp_gt_f32_e32 vcc, s16, v4
	v_mul_f32_e32 v7, 0x4f800000, v4
	ds_write2_b32 v44, v30, v6 offset0:70 offset1:86
	v_cndmask_b32_e32 v4, v4, v7, vcc
	v_sqrt_f32_e32 v7, v4
	s_nop 0
	v_add_u32_e32 v8, -1, v7
	v_fma_f32 v9, -v8, v7, v4
	v_cmp_ge_f32_e64 s[4:5], 0, v9
	v_add_u32_e32 v9, 1, v7
	s_nop 0
	v_cndmask_b32_e64 v8, v7, v8, s[4:5]
	v_fma_f32 v7, -v9, v7, v4
	v_cmp_lt_f32_e64 s[4:5], 0, v7
	s_nop 1
	v_cndmask_b32_e64 v7, v8, v9, s[4:5]
	v_mul_f32_e32 v8, 0x37800000, v7
	v_cndmask_b32_e32 v7, v7, v8, vcc
	v_cmp_class_f32_e32 vcc, v4, v205
	s_nop 1
	v_cndmask_b32_e32 v4, v7, v4, vcc
	v_mul_f32_e32 v4, v5, v4
	v_mul_f32_e32 v4, v29, v4
	ds_write2_b32 v66, v28, v4 offset0:38 offset1:54
	s_waitcnt lgkmcnt(0)
	s_barrier
; __device__ __forceinline__ void lds_barrier() { asm volatile("s_waitcnt lgkmcnt(0)" ::: "memory"); __builtin_amdgcn_s_barrier(); asm volatile("" ::: "memory"); }
; __device__ __forceinline__ void lru_item(const Params& p, int l, int item, LAS unsigned char* lds) {
;     ...
;     float Ac[16], Hl[16];
;     { float A = 1.f, H = 0.f;
; #pragma unroll
;       for (int i = 0; i < 16; ++i) { const float a = sa[i * 66 + lane], bt = xf[i * 66 + lane]; H = a * H + bt; A *= a; Ac[i] = A; Hl[i] = H; }
;       ct[(wid * 64 + lane) * 2] = A; ct[(wid * 64 + lane) * 2 + 1] = H; }
;     lds_barrier();
;     { float Ain = 1.f, Hin = 0.f;
;       for (int w = 0; w < wid; ++w) { const float aw = ct[(w * 64 + lane) * 2], hw = ct[(w * 64 + lane) * 2 + 1]; Hin = aw * Hin + hw; Ain *= aw; }
	v_add_u32_e32 v4, 0x1800, v14
	ds_read2_b32 v[22:23], v4 offset0:30 offset1:96
	ds_read_b32 v18, v80 offset:2304
	ds_read2_b32 v[6:7], v4 offset0:162 offset1:228
	v_add_u32_e32 v4, 0x800, v14
	ds_read2_b32 v[20:21], v4 offset0:130 offset1:196
	v_add_u32_e32 v4, 0x1c00, v14
	v_add_u32_e32 v5, 0xc00, v14
	ds_read2_b32 v[8:9], v4 offset0:38 offset1:104
	ds_read2_b32 v[12:13], v5 offset0:6 offset1:72
	s_waitcnt lgkmcnt(4)
	v_fmac_f32_e32 v18, 0, v23
	ds_read2_b32 v[46:47], v4 offset0:170 offset1:236
	ds_read2_b32 v[10:11], v5 offset0:138 offset1:204
	s_waitcnt lgkmcnt(4)
	v_fma_f32 v19, v18, v6, v20
	v_fmac_f32_e32 v21, v19, v7
	s_waitcnt lgkmcnt(2)
	v_fma_f32 v25, v21, v8, v12
	v_fmac_f32_e32 v13, v25, v9
	v_mul_f32_e32 v28, v23, v6
	s_waitcnt lgkmcnt(0)
	v_fma_f32 v17, v13, v46, v10
	v_add_u32_e32 v6, 0x2000, v14
	v_add_u32_e32 v10, 0x1000, v14
	ds_read2_b32 v[40:41], v6 offset0:46 offset1:112
	ds_read2_b32 v[4:5], v10 offset0:14 offset1:80
	ds_read2_b32 v[38:39], v6 offset0:178 offset1:244
	ds_read2_b32 v[42:43], v10 offset0:146 offset1:212
	v_fmac_f32_e32 v11, v17, v47
	v_mov_b32_e32 v6, v7
	v_mov_b32_e32 v26, v8
	s_waitcnt lgkmcnt(2)
	v_fma_f32 v15, v11, v40, v4
	v_fmac_f32_e32 v5, v15, v41
	v_mov_b32_e32 v29, v5
	s_waitcnt lgkmcnt(1)
	v_mov_b32_e32 v7, v38
	v_add_u32_e32 v4, 0x2400, v14
	v_pk_mul_f32 v[32:33], v[28:29], v[6:7]
	s_waitcnt lgkmcnt(0)
	v_mov_b32_e32 v27, v42
	ds_read2_b32 v[48:49], v4 offset0:54 offset1:120
	v_pk_mul_f32 v[36:37], v[32:33], v[26:27]
	v_pk_fma_f32 v[6:7], v[28:29], v[6:7], v[26:27]
	v_mov_b32_e32 v8, v9
	v_mov_b32_e32 v37, v7
	v_mov_b32_e32 v9, v39
	v_pk_mul_f32 v[26:27], v[36:37], v[8:9]
	v_mov_b32_e32 v42, v46
	v_add_u32_e32 v6, 0x1400, v14
	v_pk_mul_f32 v[30:31], v[26:27], v[42:43]
	v_pk_fma_f32 v[8:9], v[36:37], v[8:9], v[42:43]
	ds_read2_b32 v[50:51], v6 offset0:22 offset1:88
	ds_read2_b32 v[42:43], v4 offset0:186 offset1:252
	ds_read2_b32 v[44:45], v6 offset0:154 offset1:220
	ds_read_b32 v67, v14 offset:10488
	v_mov_b32_e32 v31, v9
	v_mov_b32_e32 v46, v47
	s_waitcnt lgkmcnt(4)
	v_mov_b32_e32 v47, v48
	v_pk_mul_f32 v[60:61], v[30:31], v[46:47]
	v_mov_b32_e32 v52, v40
	s_waitcnt lgkmcnt(3)
	v_mov_b32_e32 v53, v50
	v_pk_mul_f32 v[64:65], v[60:61], v[52:53]
	v_pk_fma_f32 v[52:53], v[30:31], v[46:47], v[52:53]
	v_mov_b32_e32 v40, v41
	v_mov_b32_e32 v65, v53
	v_mov_b32_e32 v41, v49
	v_pk_mul_f32 v[54:55], v[64:65], v[40:41]
	v_mov_b32_e32 v50, v38
	v_pk_mul_f32 v[58:59], v[54:55], v[50:51]
	v_pk_fma_f32 v[40:41], v[64:65], v[40:41], v[50:51]
	v_mov_b32_e32 v38, v39
	v_mov_b32_e32 v59, v41
	s_waitcnt lgkmcnt(2)
	v_mov_b32_e32 v39, v42
	v_pk_mul_f32 v[56:57], v[58:59], v[38:39]
	v_mov_b32_e32 v46, v48
	s_waitcnt lgkmcnt(1)
	v_mov_b32_e32 v47, v44
	v_pk_mul_f32 v[62:63], v[56:57], v[46:47]
	v_pk_fma_f32 v[46:47], v[58:59], v[38:39], v[46:47]
	v_mov_b32_e32 v38, v49
	v_mov_b32_e32 v63, v47
	v_mov_b32_e32 v39, v43
	v_pk_mul_f32 v[48:49], v[62:63], v[38:39]
	v_mov_b32_e32 v44, v42
	v_pk_mul_f32 v[50:51], v[48:49], v[44:45]
	v_pk_fma_f32 v[38:39], v[62:63], v[38:39], v[44:45]
	v_mov_b32_e32 v66, v43
	v_mov_b32_e32 v51, v39
	s_waitcnt lgkmcnt(0)
	v_pk_mul_f32 v[44:45], v[50:51], v[66:67]
	v_mov_b32_e32 v68, v67
	v_mov_b32_e32 v69, v22
	v_pk_mul_f32 v[42:43], v[44:45], v[68:69]
	v_pk_fma_f32 v[66:67], v[50:51], v[66:67], v[68:69]
	v_mul_f32_e32 v34, 0, v23
	v_mov_b32_e32 v43, v67
	ds_write_b64 v1, v[42:43]
	s_waitcnt lgkmcnt(0)
	s_barrier
	v_cmp_lt_i32_e32 vcc, 0, v0
	v_mov_b32_e32 v8, 1.0
	s_and_saveexec_b64 s[4:5], vcc
	s_cbranch_execz .LBB0_397
	v_readlane_b32 s6, v255, 9
	v_mov_b32_e32 v8, 1.0
	v_mov_b32_e32 v77, 0
	v_lshl_add_u32 v1, v3, 3, s6
	s_mov_b64 s[6:7], 0
	v_mov_b32_e32 v4, v0
